# baseline (speedup 1.0000x reference)
; __device__ __forceinline__ void sb_phase(const Params& p, char* shm, int wv, int vb) {
;     ...
;       if (tile <= lastTile && !mydone) {
;         const char* Kb = shm + sl * SB_SLOT;
;         const char* Vb = Kb + 9216;
;         const int key0 = tile * 64;
;         if (key0 == q0) sb_step<1>(Kb, Vb, qf, U, oacc, carry, key0, q0, fr, fq);
;         else if (key0 + 32 == q0) sb_step<2>(Kb, Vb, qf, U, oacc, carry, key0, q0, fr, fq);
;         else sb_step<0>(Kb, Vb, qf, U, oacc, carry, key0, q0, fr, fq);
;         mydone = __all((carry[0] >= SB_DONE) && (carry[1] >= SB_DONE)) != 0;
.LBB0_391:
	s_or_b64 exec, exec, s[10:11]
	v_cmp_le_f32_e64 s[10:11], s86, v84
	v_cmp_le_f32_e64 s[12:13], s86, v96
	s_and_b64 s[10:11], s[10:11], s[12:13]
	s_cmp_eq_u64 s[10:11], exec
	s_cselect_b64 s[10:11], -1, 0
	s_andn2_b64 s[12:13], s[70:71], exec
	s_and_b64 s[10:11], s[10:11], exec
	s_or_b64 s[70:71], s[12:13], s[10:11]
